# v14 plus P1 row phase: modulation vectors (g, scale, shift) loaded in one burst instead of 8 serialized rounds
# baseline (speedup 1.0000x reference)
; template <bool FINAL>
; __device__ __forceinline__ void rows_phase(const float* srcL, const float* srcC, int nL, int nTot, const float* g, const float* mod, int sh_off, int sc_off, void* dst, int gw, int NGW, int lane) {
;     ...
;         if (mr != cur) { cur = mr;
; #pragma unroll
;             for (int j = 0; j < 8; ++j) { const int o = j * 256 + lane * 4; const f32x4 gg = *(const f32x4*)(g + o);
;                 if (FINAL) { A[j] = gg; B[j] = (f32x4){0.f, 0.f, 0.f, 0.f}; }
;                 else { const float* mp = mod + (size_t)mr * NMOD + o; A[j] = gg * (*(const f32x4*)(mp + sc_off) + 1.0f); B[j] = *(const f32x4*)(mp + sh_off); } } }
.LBB0_129:
	v_mad_i64_i32 v[104:105], s[12:13], s0, v146, v[132:133]
	s_mov_b32 s9, s0
	v_add_co_u32_e32 v48, vcc, 0x2000, v104
	s_nop 1
	v_addc_co_u32_e32 v49, vcc, 0, v105, vcc
	v_add_co_u32_e32 v124, vcc, s7, v104
	s_nop 1
	v_addc_co_u32_e32 v125, vcc, 0, v105, vcc
	v_add_co_u32_e32 v158, vcc, s6, v104
	s_nop 1
	v_addc_co_u32_e32 v159, vcc, 0, v105, vcc
	global_load_dwordx4 v[200:203], v[48:49], off
	global_load_dwordx4 v[204:207], v[48:49], off offset:1024
	global_load_dwordx4 v[208:211], v[48:49], off offset:2048
	global_load_dwordx4 v[212:215], v[48:49], off offset:3072
	global_load_dwordx4 v[216:219], v[124:125], off
	global_load_dwordx4 v[220:223], v[124:125], off offset:1024
	global_load_dwordx4 v[224:227], v[124:125], off offset:2048
	global_load_dwordx4 v[228:231], v[124:125], off offset:3072
	global_load_dwordx4 v[52:55], v[104:105], off
	global_load_dwordx4 v[56:59], v[104:105], off offset:1024
	global_load_dwordx4 v[60:63], v[104:105], off offset:2048
	global_load_dwordx4 v[64:67], v[104:105], off offset:3072
	global_load_dwordx4 v[112:115], v[158:159], off
	global_load_dwordx4 v[116:119], v[158:159], off offset:1024
	global_load_dwordx4 v[120:123], v[158:159], off offset:2048
	global_load_dwordx4 v[124:127], v[158:159], off offset:3072
	global_load_dwordx4 v[44:47], v[130:131], off
	global_load_dwordx4 v[8:11], v[130:131], off offset:1024
	global_load_dwordx4 v[12:15], v[130:131], off offset:2048
	global_load_dwordx4 v[16:19], v[130:131], off offset:3072
	global_load_dwordx4 v[48:51], v[134:135], off
	global_load_dwordx4 v[68:71], v[136:137], off
	global_load_dwordx4 v[104:107], v[138:139], off
	global_load_dwordx4 v[108:111], v[140:141], off
	s_waitcnt vmcnt(0)
	v_pk_add_f32 v[202:203], v[202:203], 1.0 op_sel_hi:[1,0]
	v_pk_add_f32 v[200:201], v[200:201], 1.0 op_sel_hi:[1,0]
	v_pk_add_f32 v[206:207], v[206:207], 1.0 op_sel_hi:[1,0]
	v_pk_add_f32 v[204:205], v[204:205], 1.0 op_sel_hi:[1,0]
	v_pk_add_f32 v[210:211], v[210:211], 1.0 op_sel_hi:[1,0]
	v_pk_add_f32 v[208:209], v[208:209], 1.0 op_sel_hi:[1,0]
	v_pk_add_f32 v[214:215], v[214:215], 1.0 op_sel_hi:[1,0]
	v_pk_add_f32 v[212:213], v[212:213], 1.0 op_sel_hi:[1,0]
	v_pk_add_f32 v[218:219], v[218:219], 1.0 op_sel_hi:[1,0]
	v_pk_add_f32 v[216:217], v[216:217], 1.0 op_sel_hi:[1,0]
	v_pk_add_f32 v[222:223], v[222:223], 1.0 op_sel_hi:[1,0]
	v_pk_add_f32 v[220:221], v[220:221], 1.0 op_sel_hi:[1,0]
	v_pk_add_f32 v[226:227], v[226:227], 1.0 op_sel_hi:[1,0]
	v_pk_add_f32 v[224:225], v[224:225], 1.0 op_sel_hi:[1,0]
	v_pk_add_f32 v[230:231], v[230:231], 1.0 op_sel_hi:[1,0]
	v_pk_add_f32 v[228:229], v[228:229], 1.0 op_sel_hi:[1,0]
	v_pk_mul_f32 v[46:47], v[46:47], v[202:203]
	v_pk_mul_f32 v[44:45], v[44:45], v[200:201]
	v_pk_mul_f32 v[10:11], v[10:11], v[206:207]
	v_pk_mul_f32 v[8:9], v[8:9], v[204:205]
	v_pk_mul_f32 v[14:15], v[14:15], v[210:211]
	v_pk_mul_f32 v[12:13], v[12:13], v[208:209]
	v_pk_mul_f32 v[18:19], v[18:19], v[214:215]
	v_pk_mul_f32 v[16:17], v[16:17], v[212:213]
	v_pk_mul_f32 v[50:51], v[50:51], v[218:219]
	v_pk_mul_f32 v[48:49], v[48:49], v[216:217]
	v_pk_mul_f32 v[70:71], v[70:71], v[222:223]
	v_pk_mul_f32 v[68:69], v[68:69], v[220:221]
	v_pk_mul_f32 v[106:107], v[106:107], v[226:227]
	v_pk_mul_f32 v[104:105], v[104:105], v[224:225]
	v_pk_mul_f32 v[110:111], v[110:111], v[230:231]
	v_pk_mul_f32 v[108:109], v[108:109], v[228:229]
	s_branch .LBB0_123
